# layer-1 RMSNorm also fused into layer-0 out-projection epilogue (x_next + H written after the barrier; norm phase of layer 1 skipped)
# speedup vs baseline: 1.0397x; 1.0152x over previous
.LBB0_177:
	s_or_b64 exec, exec, s[0:1]
	v_readlane_b32 s0, v252, 23
	s_nop 3
	s_cmp_eq_u32 s0, 0
	s_cbranch_scc1 .Lfz_l1
	s_barrier
	s_add_u32 s44, s96, 0x6000000
	s_addc_u32 s45, s97, 0
	v_lshlrev_b32_e32 v158, 4, v148
	global_load_dwordx4 v[0:3], v158, s[44:45] offset:0
	global_load_dwordx4 v[4:7], v158, s[44:45] offset:256
	global_load_dwordx4 v[8:11], v158, s[44:45] offset:512
	global_load_dwordx4 v[12:15], v158, s[44:45] offset:768
	global_load_dwordx4 v[16:19], v158, s[44:45] offset:2048
	global_load_dwordx4 v[120:123], v158, s[44:45] offset:2304
	global_load_dwordx4 v[124:127], v158, s[44:45] offset:2560
	global_load_dwordx4 v[154:157], v158, s[44:45] offset:2816
	v_mov_b32_e32 v159, 0x358637bd
	s_mov_b32 s42, 0x800000
	s_waitcnt vmcnt(0)
	v_add_f32_e32 v0, v0, v1
	v_add_f32_e32 v0, v0, v2
	v_add_f32_e32 v0, v0, v3
	v_fmamk_f32 v0, v0, 0x3a800000, v159
	v_mul_f32_e32 v1, 0x4b800000, v0
	v_cmp_gt_f32_e32 vcc, s42, v0
	s_nop 1
	v_cndmask_b32_e32 v0, v0, v1, vcc
	v_rsq_f32_e32 v0, v0
	s_nop 0
	v_mul_f32_e32 v1, 0x45800000, v0
	v_cndmask_b32_e32 v184, v0, v1, vcc
	v_add_f32_e32 v4, v4, v5
	v_add_f32_e32 v4, v4, v6
	v_add_f32_e32 v4, v4, v7
	v_fmamk_f32 v4, v4, 0x3a800000, v159
	v_mul_f32_e32 v5, 0x4b800000, v4
	v_cmp_gt_f32_e32 vcc, s42, v4
	s_nop 1
	v_cndmask_b32_e32 v4, v4, v5, vcc
	v_rsq_f32_e32 v4, v4
	s_nop 0
	v_mul_f32_e32 v5, 0x45800000, v4
	v_cndmask_b32_e32 v186, v4, v5, vcc
	v_add_f32_e32 v8, v8, v9
	v_add_f32_e32 v8, v8, v10
	v_add_f32_e32 v8, v8, v11
	v_fmamk_f32 v8, v8, 0x3a800000, v159
	v_mul_f32_e32 v9, 0x4b800000, v8
	v_cmp_gt_f32_e32 vcc, s42, v8
	s_nop 1
	v_cndmask_b32_e32 v8, v8, v9, vcc
	v_rsq_f32_e32 v8, v8
	s_nop 0
	v_mul_f32_e32 v9, 0x45800000, v8
	v_cndmask_b32_e32 v188, v8, v9, vcc
	v_add_f32_e32 v12, v12, v13
	v_add_f32_e32 v12, v12, v14
	v_add_f32_e32 v12, v12, v15
	v_fmamk_f32 v12, v12, 0x3a800000, v159
	v_mul_f32_e32 v13, 0x4b800000, v12
	v_cmp_gt_f32_e32 vcc, s42, v12
	s_nop 1
	v_cndmask_b32_e32 v12, v12, v13, vcc
	v_rsq_f32_e32 v12, v12
	s_nop 0
	v_mul_f32_e32 v13, 0x45800000, v12
	v_cndmask_b32_e32 v190, v12, v13, vcc
	v_add_f32_e32 v16, v16, v17
	v_add_f32_e32 v16, v16, v18
	v_add_f32_e32 v16, v16, v19
	v_fmamk_f32 v16, v16, 0x3a800000, v159
	v_mul_f32_e32 v17, 0x4b800000, v16
	v_cmp_gt_f32_e32 vcc, s42, v16
	s_nop 1
	v_cndmask_b32_e32 v16, v16, v17, vcc
	v_rsq_f32_e32 v16, v16
	s_nop 0
	v_mul_f32_e32 v17, 0x45800000, v16
	v_cndmask_b32_e32 v16, v16, v17, vcc
	v_add_f32_e32 v120, v120, v121
	v_add_f32_e32 v120, v120, v122
	v_add_f32_e32 v120, v120, v123
	v_fmamk_f32 v120, v120, 0x3a800000, v159
	v_mul_f32_e32 v121, 0x4b800000, v120
	v_cmp_gt_f32_e32 vcc, s42, v120
	s_nop 1
	v_cndmask_b32_e32 v120, v120, v121, vcc
	v_rsq_f32_e32 v120, v120
	s_nop 0
	v_mul_f32_e32 v121, 0x45800000, v120
	v_cndmask_b32_e32 v18, v120, v121, vcc
	v_add_f32_e32 v124, v124, v125
	v_add_f32_e32 v124, v124, v126
	v_add_f32_e32 v124, v124, v127
	v_fmamk_f32 v124, v124, 0x3a800000, v159
	v_mul_f32_e32 v125, 0x4b800000, v124
	v_cmp_gt_f32_e32 vcc, s42, v124
	s_nop 1
	v_cndmask_b32_e32 v124, v124, v125, vcc
	v_rsq_f32_e32 v124, v124
	s_nop 0
	v_mul_f32_e32 v125, 0x45800000, v124
	v_cndmask_b32_e32 v142, v124, v125, vcc
	v_add_f32_e32 v154, v154, v155
	v_add_f32_e32 v154, v154, v156
	v_add_f32_e32 v154, v154, v157
	v_fmamk_f32 v154, v154, 0x3a800000, v159
	v_mul_f32_e32 v155, 0x4b800000, v154
	v_cmp_gt_f32_e32 vcc, s42, v154
	s_nop 1
	v_cndmask_b32_e32 v154, v154, v155, vcc
	v_rsq_f32_e32 v154, v154
	s_nop 0
	v_mul_f32_e32 v155, 0x45800000, v154
	v_cndmask_b32_e32 v144, v154, v155, vcc
	v_readlane_b32 s0, v253, 14
	v_readlane_b32 s1, v253, 15
	s_nop 3
	s_add_u32 s0, s0, 0x1000
	s_addc_u32 s1, s1, 0
	v_lshl_add_u64 v[160:161], s[0:1], 0, v[146:147]
	v_lshrrev_b32_e32 v216, 12, v148
	v_mul_u32_u24_e32 v216, 0x3000, v216
	v_mov_b32_e32 v217, 0
	s_add_u32 s0, s96, 0x10acc000
	s_addc_u32 s1, s97, 0
	v_lshl_add_u64 v[216:217], s[0:1], 0, v[216:217]
	v_lshl_add_u64 v[216:217], v[216:217], 0, v[146:147]
	s_mov_b64 s[0:1], 0x1000
	v_lshl_add_u64 v[192:193], v[216:217], 0, s[0:1]
	global_load_dwordx4 v[0:3], v[160:161], off offset:16
	global_load_dwordx4 v[4:7], v[160:161], off offset:0
	global_load_dwordx4 v[8:11], v[160:161], off offset:528
	global_load_dwordx4 v[12:15], v[160:161], off offset:512
	global_load_dwordx4 v[236:239], v[192:193], off offset:16
	global_load_dwordx4 v[240:243], v[192:193], off offset:0
	global_load_dwordx4 v[244:247], v[192:193], off offset:528
	global_load_dwordx4 v[248:251], v[192:193], off offset:512
	global_load_dwordx4 v[120:123], v[216:217], off offset:16
	global_load_dwordx4 v[124:127], v[216:217], off offset:0
	global_load_dwordx4 v[154:157], v[216:217], off offset:528
	global_load_dwordx4 v[158:161], v[216:217], off offset:512
	v_lshlrev_b32_e32 v162, 12, v148
	v_mov_b32_e32 v163, 0
	v_lshl_add_u64 v[162:163], s[94:95], 0, v[162:163]
	v_lshl_add_u64 v[162:163], v[162:163], 0, v[146:147]
	v_lshlrev_b32_e32 v140, 11, v148
	v_lshrrev_b32_e32 v141, 1, v146
	v_add_u32_e32 v140, v140, v141
	v_mov_b32_e32 v141, 0
	s_add_u32 s0, s96, 0xb000000
	s_addc_u32 s1, s97, 0
	v_lshl_add_u64 v[140:141], s[0:1], 0, v[140:141]
	s_waitcnt vmcnt(4)
	v_pk_fma_f32 v[0:1], v[0:1], v[236:237], v[0:1]
	v_pk_fma_f32 v[2:3], v[2:3], v[238:239], v[2:3]
	v_pk_fma_f32 v[4:5], v[4:5], v[240:241], v[4:5]
	v_pk_fma_f32 v[6:7], v[6:7], v[242:243], v[6:7]
	v_pk_fma_f32 v[8:9], v[8:9], v[244:245], v[8:9]
	v_pk_fma_f32 v[10:11], v[10:11], v[246:247], v[10:11]
	v_pk_fma_f32 v[12:13], v[12:13], v[248:249], v[12:13]
	v_pk_fma_f32 v[14:15], v[14:15], v[250:251], v[14:15]
	s_waitcnt vmcnt(0)
	global_store_dwordx4 v[162:163], v[128:131], off offset:16
	global_store_dwordx4 v[162:163], v[132:135], off offset:0
	v_pk_mul_f32 v[236:237], v[132:133], v[184:185] op_sel_hi:[1,0]
	v_pk_mul_f32 v[238:239], v[134:135], v[184:185] op_sel_hi:[1,0]
	v_pk_fma_f32 v[236:237], v[236:237], v[4:5], v[124:125]
	v_pk_fma_f32 v[238:239], v[238:239], v[6:7], v[126:127]
	v_cvt_pk_bf16_f32 v244, v236, v237
	v_cvt_pk_bf16_f32 v245, v238, v239
	v_pk_mul_f32 v[236:237], v[128:129], v[184:185] op_sel_hi:[1,0]
	v_pk_mul_f32 v[238:239], v[130:131], v[184:185] op_sel_hi:[1,0]
	v_pk_fma_f32 v[236:237], v[236:237], v[0:1], v[120:121]
	v_pk_fma_f32 v[238:239], v[238:239], v[2:3], v[122:123]
	v_cvt_pk_bf16_f32 v246, v236, v237
	v_cvt_pk_bf16_f32 v247, v238, v239
	global_store_dwordx4 v[140:141], v[244:247], off offset:0
	global_store_dwordx4 v[162:163], v[56:59], off offset:528
	global_store_dwordx4 v[162:163], v[64:67], off offset:512
	v_pk_mul_f32 v[236:237], v[64:65], v[184:185] op_sel_hi:[1,0]
	v_pk_mul_f32 v[238:239], v[66:67], v[184:185] op_sel_hi:[1,0]
	v_pk_fma_f32 v[236:237], v[236:237], v[12:13], v[158:159]
	v_pk_fma_f32 v[238:239], v[238:239], v[14:15], v[160:161]
	v_cvt_pk_bf16_f32 v248, v236, v237
	v_cvt_pk_bf16_f32 v249, v238, v239
	v_pk_mul_f32 v[236:237], v[56:57], v[184:185] op_sel_hi:[1,0]
	v_pk_mul_f32 v[238:239], v[58:59], v[184:185] op_sel_hi:[1,0]
	v_pk_fma_f32 v[236:237], v[236:237], v[8:9], v[154:155]
	v_pk_fma_f32 v[238:239], v[238:239], v[10:11], v[156:157]
	v_cvt_pk_bf16_f32 v250, v236, v237
	v_cvt_pk_bf16_f32 v251, v238, v239
	global_store_dwordx4 v[140:141], v[248:251], off offset:256
	s_mov_b64 s[0:1], 0x10000
	v_lshl_add_u64 v[212:213], v[162:163], 0, s[0:1]
	s_mov_b64 s[0:1], 0x8000
	v_lshl_add_u64 v[136:137], v[140:141], 0, s[0:1]
	global_store_dwordx4 v[212:213], v[112:115], off offset:16
	global_store_dwordx4 v[212:213], v[116:119], off offset:0
	v_pk_mul_f32 v[236:237], v[116:117], v[186:187] op_sel_hi:[1,0]
	v_pk_mul_f32 v[238:239], v[118:119], v[186:187] op_sel_hi:[1,0]
	v_pk_fma_f32 v[236:237], v[236:237], v[4:5], v[124:125]
	v_pk_fma_f32 v[238:239], v[238:239], v[6:7], v[126:127]
	v_cvt_pk_bf16_f32 v244, v236, v237
	v_cvt_pk_bf16_f32 v245, v238, v239
	v_pk_mul_f32 v[236:237], v[112:113], v[186:187] op_sel_hi:[1,0]
	v_pk_mul_f32 v[238:239], v[114:115], v[186:187] op_sel_hi:[1,0]
	v_pk_fma_f32 v[236:237], v[236:237], v[0:1], v[120:121]
	v_pk_fma_f32 v[238:239], v[238:239], v[2:3], v[122:123]
	v_cvt_pk_bf16_f32 v246, v236, v237
	v_cvt_pk_bf16_f32 v247, v238, v239
	global_store_dwordx4 v[136:137], v[244:247], off offset:0
	global_store_dwordx4 v[212:213], v[48:51], off offset:528
	global_store_dwordx4 v[212:213], v[52:55], off offset:512
	v_pk_mul_f32 v[236:237], v[52:53], v[186:187] op_sel_hi:[1,0]
	v_pk_mul_f32 v[238:239], v[54:55], v[186:187] op_sel_hi:[1,0]
	v_pk_fma_f32 v[236:237], v[236:237], v[12:13], v[158:159]
	v_pk_fma_f32 v[238:239], v[238:239], v[14:15], v[160:161]
	v_cvt_pk_bf16_f32 v248, v236, v237
	v_cvt_pk_bf16_f32 v249, v238, v239
	v_pk_mul_f32 v[236:237], v[48:49], v[186:187] op_sel_hi:[1,0]
	v_pk_mul_f32 v[238:239], v[50:51], v[186:187] op_sel_hi:[1,0]
	v_pk_fma_f32 v[236:237], v[236:237], v[8:9], v[154:155]
	v_pk_fma_f32 v[238:239], v[238:239], v[10:11], v[156:157]
	v_cvt_pk_bf16_f32 v250, v236, v237
	v_cvt_pk_bf16_f32 v251, v238, v239
	global_store_dwordx4 v[136:137], v[248:251], off offset:256
	s_mov_b64 s[0:1], 0x20000
	v_lshl_add_u64 v[214:215], v[162:163], 0, s[0:1]
	s_mov_b64 s[0:1], 0x10000
	v_lshl_add_u64 v[138:139], v[140:141], 0, s[0:1]
	global_store_dwordx4 v[214:215], v[104:107], off offset:16
	global_store_dwordx4 v[214:215], v[108:111], off offset:0
	v_pk_mul_f32 v[236:237], v[108:109], v[188:189] op_sel_hi:[1,0]
	v_pk_mul_f32 v[238:239], v[110:111], v[188:189] op_sel_hi:[1,0]
	v_pk_fma_f32 v[236:237], v[236:237], v[4:5], v[124:125]
	v_pk_fma_f32 v[238:239], v[238:239], v[6:7], v[126:127]
	v_cvt_pk_bf16_f32 v244, v236, v237
	v_cvt_pk_bf16_f32 v245, v238, v239
	v_pk_mul_f32 v[236:237], v[104:105], v[188:189] op_sel_hi:[1,0]
	v_pk_mul_f32 v[238:239], v[106:107], v[188:189] op_sel_hi:[1,0]
	v_pk_fma_f32 v[236:237], v[236:237], v[0:1], v[120:121]
	v_pk_fma_f32 v[238:239], v[238:239], v[2:3], v[122:123]
	v_cvt_pk_bf16_f32 v246, v236, v237
	v_cvt_pk_bf16_f32 v247, v238, v239
	global_store_dwordx4 v[138:139], v[244:247], off offset:0
	global_store_dwordx4 v[214:215], v[40:43], off offset:528
	global_store_dwordx4 v[214:215], v[44:47], off offset:512
	v_pk_mul_f32 v[236:237], v[44:45], v[188:189] op_sel_hi:[1,0]
	v_pk_mul_f32 v[238:239], v[46:47], v[188:189] op_sel_hi:[1,0]
	v_pk_fma_f32 v[236:237], v[236:237], v[12:13], v[158:159]
	v_pk_fma_f32 v[238:239], v[238:239], v[14:15], v[160:161]
	v_cvt_pk_bf16_f32 v248, v236, v237
	v_cvt_pk_bf16_f32 v249, v238, v239
	v_pk_mul_f32 v[236:237], v[40:41], v[188:189] op_sel_hi:[1,0]
	v_pk_mul_f32 v[238:239], v[42:43], v[188:189] op_sel_hi:[1,0]
	v_pk_fma_f32 v[236:237], v[236:237], v[8:9], v[154:155]
	v_pk_fma_f32 v[238:239], v[238:239], v[10:11], v[156:157]
	v_cvt_pk_bf16_f32 v250, v236, v237
	v_cvt_pk_bf16_f32 v251, v238, v239
	global_store_dwordx4 v[138:139], v[248:251], off offset:256
	s_mov_b64 s[0:1], 0x30000
	v_lshl_add_u64 v[212:213], v[162:163], 0, s[0:1]
	s_mov_b64 s[0:1], 0x18000
	v_lshl_add_u64 v[136:137], v[140:141], 0, s[0:1]
	global_store_dwordx4 v[212:213], v[96:99], off offset:16
	global_store_dwordx4 v[212:213], v[100:103], off offset:0
	v_pk_mul_f32 v[236:237], v[100:101], v[190:191] op_sel_hi:[1,0]
	v_pk_mul_f32 v[238:239], v[102:103], v[190:191] op_sel_hi:[1,0]
	v_pk_fma_f32 v[236:237], v[236:237], v[4:5], v[124:125]
	v_pk_fma_f32 v[238:239], v[238:239], v[6:7], v[126:127]
	v_cvt_pk_bf16_f32 v244, v236, v237
	v_cvt_pk_bf16_f32 v245, v238, v239
	v_pk_mul_f32 v[236:237], v[96:97], v[190:191] op_sel_hi:[1,0]
	v_pk_mul_f32 v[238:239], v[98:99], v[190:191] op_sel_hi:[1,0]
	v_pk_fma_f32 v[236:237], v[236:237], v[0:1], v[120:121]
	v_pk_fma_f32 v[238:239], v[238:239], v[2:3], v[122:123]
	v_cvt_pk_bf16_f32 v246, v236, v237
	v_cvt_pk_bf16_f32 v247, v238, v239
	global_store_dwordx4 v[136:137], v[244:247], off offset:0
	global_store_dwordx4 v[212:213], v[32:35], off offset:528
	global_store_dwordx4 v[212:213], v[36:39], off offset:512
	v_pk_mul_f32 v[236:237], v[36:37], v[190:191] op_sel_hi:[1,0]
	v_pk_mul_f32 v[238:239], v[38:39], v[190:191] op_sel_hi:[1,0]
	v_pk_fma_f32 v[236:237], v[236:237], v[12:13], v[158:159]
	v_pk_fma_f32 v[238:239], v[238:239], v[14:15], v[160:161]
	v_cvt_pk_bf16_f32 v248, v236, v237
	v_cvt_pk_bf16_f32 v249, v238, v239
	v_pk_mul_f32 v[236:237], v[32:33], v[190:191] op_sel_hi:[1,0]
	v_pk_mul_f32 v[238:239], v[34:35], v[190:191] op_sel_hi:[1,0]
	v_pk_fma_f32 v[236:237], v[236:237], v[8:9], v[154:155]
	v_pk_fma_f32 v[238:239], v[238:239], v[10:11], v[156:157]
	v_cvt_pk_bf16_f32 v250, v236, v237
	v_cvt_pk_bf16_f32 v251, v238, v239
	global_store_dwordx4 v[136:137], v[248:251], off offset:256
	s_mov_b64 s[0:1], 0x80000
	v_lshl_add_u64 v[214:215], v[162:163], 0, s[0:1]
	s_mov_b64 s[0:1], 0x40000
	v_lshl_add_u64 v[138:139], v[140:141], 0, s[0:1]
	global_store_dwordx4 v[214:215], v[88:91], off offset:16
	global_store_dwordx4 v[214:215], v[92:95], off offset:0
	v_pk_mul_f32 v[236:237], v[92:93], v[16:17] op_sel_hi:[1,0]
	v_pk_mul_f32 v[238:239], v[94:95], v[16:17] op_sel_hi:[1,0]
	v_pk_fma_f32 v[236:237], v[236:237], v[4:5], v[124:125]
	v_pk_fma_f32 v[238:239], v[238:239], v[6:7], v[126:127]
	v_cvt_pk_bf16_f32 v244, v236, v237
	v_cvt_pk_bf16_f32 v245, v238, v239
	v_pk_mul_f32 v[236:237], v[88:89], v[16:17] op_sel_hi:[1,0]
	v_pk_mul_f32 v[238:239], v[90:91], v[16:17] op_sel_hi:[1,0]
	v_pk_fma_f32 v[236:237], v[236:237], v[0:1], v[120:121]
	v_pk_fma_f32 v[238:239], v[238:239], v[2:3], v[122:123]
	v_cvt_pk_bf16_f32 v246, v236, v237
	v_cvt_pk_bf16_f32 v247, v238, v239
	global_store_dwordx4 v[138:139], v[244:247], off offset:0
	global_store_dwordx4 v[214:215], v[24:27], off offset:528
	global_store_dwordx4 v[214:215], v[28:31], off offset:512
	v_pk_mul_f32 v[236:237], v[28:29], v[16:17] op_sel_hi:[1,0]
	v_pk_mul_f32 v[238:239], v[30:31], v[16:17] op_sel_hi:[1,0]
	v_pk_fma_f32 v[236:237], v[236:237], v[12:13], v[158:159]
	v_pk_fma_f32 v[238:239], v[238:239], v[14:15], v[160:161]
	v_cvt_pk_bf16_f32 v248, v236, v237
	v_cvt_pk_bf16_f32 v249, v238, v239
	v_pk_mul_f32 v[236:237], v[24:25], v[16:17] op_sel_hi:[1,0]
	v_pk_mul_f32 v[238:239], v[26:27], v[16:17] op_sel_hi:[1,0]
	v_pk_fma_f32 v[236:237], v[236:237], v[8:9], v[154:155]
	v_pk_fma_f32 v[238:239], v[238:239], v[10:11], v[156:157]
	v_cvt_pk_bf16_f32 v250, v236, v237
	v_cvt_pk_bf16_f32 v251, v238, v239
	global_store_dwordx4 v[138:139], v[248:251], off offset:256
	s_mov_b64 s[0:1], 0x90000
	v_lshl_add_u64 v[212:213], v[162:163], 0, s[0:1]
	s_mov_b64 s[0:1], 0x48000
	v_lshl_add_u64 v[136:137], v[140:141], 0, s[0:1]
	global_store_dwordx4 v[212:213], v[80:83], off offset:16
	global_store_dwordx4 v[212:213], v[84:87], off offset:0
	v_pk_mul_f32 v[236:237], v[84:85], v[18:19] op_sel_hi:[1,0]
	v_pk_mul_f32 v[238:239], v[86:87], v[18:19] op_sel_hi:[1,0]
	v_pk_fma_f32 v[236:237], v[236:237], v[4:5], v[124:125]
	v_pk_fma_f32 v[238:239], v[238:239], v[6:7], v[126:127]
	v_cvt_pk_bf16_f32 v244, v236, v237
	v_cvt_pk_bf16_f32 v245, v238, v239
	v_pk_mul_f32 v[236:237], v[80:81], v[18:19] op_sel_hi:[1,0]
	v_pk_mul_f32 v[238:239], v[82:83], v[18:19] op_sel_hi:[1,0]
	v_pk_fma_f32 v[236:237], v[236:237], v[0:1], v[120:121]
	v_pk_fma_f32 v[238:239], v[238:239], v[2:3], v[122:123]
	v_cvt_pk_bf16_f32 v246, v236, v237
	v_cvt_pk_bf16_f32 v247, v238, v239
	global_store_dwordx4 v[136:137], v[244:247], off offset:0
	global_store_dwordx4 v[212:213], v[180:183], off offset:528
	global_store_dwordx4 v[212:213], v[20:23], off offset:512
	v_pk_mul_f32 v[236:237], v[20:21], v[18:19] op_sel_hi:[1,0]
	v_pk_mul_f32 v[238:239], v[22:23], v[18:19] op_sel_hi:[1,0]
	v_pk_fma_f32 v[236:237], v[236:237], v[12:13], v[158:159]
	v_pk_fma_f32 v[238:239], v[238:239], v[14:15], v[160:161]
	v_cvt_pk_bf16_f32 v248, v236, v237
	v_cvt_pk_bf16_f32 v249, v238, v239
	v_pk_mul_f32 v[236:237], v[180:181], v[18:19] op_sel_hi:[1,0]
	v_pk_mul_f32 v[238:239], v[182:183], v[18:19] op_sel_hi:[1,0]
	v_pk_fma_f32 v[236:237], v[236:237], v[8:9], v[154:155]
	v_pk_fma_f32 v[238:239], v[238:239], v[10:11], v[156:157]
	v_cvt_pk_bf16_f32 v250, v236, v237
	v_cvt_pk_bf16_f32 v251, v238, v239
	global_store_dwordx4 v[136:137], v[248:251], off offset:256
	s_mov_b64 s[0:1], 0xa0000
	v_lshl_add_u64 v[214:215], v[162:163], 0, s[0:1]
	s_mov_b64 s[0:1], 0x50000
	v_lshl_add_u64 v[138:139], v[140:141], 0, s[0:1]
	global_store_dwordx4 v[214:215], v[72:75], off offset:16
	global_store_dwordx4 v[214:215], v[76:79], off offset:0
	v_pk_mul_f32 v[236:237], v[76:77], v[142:143] op_sel_hi:[1,0]
	v_pk_mul_f32 v[238:239], v[78:79], v[142:143] op_sel_hi:[1,0]
	v_pk_fma_f32 v[236:237], v[236:237], v[4:5], v[124:125]
	v_pk_fma_f32 v[238:239], v[238:239], v[6:7], v[126:127]
	v_cvt_pk_bf16_f32 v244, v236, v237
	v_cvt_pk_bf16_f32 v245, v238, v239
	v_pk_mul_f32 v[236:237], v[72:73], v[142:143] op_sel_hi:[1,0]
	v_pk_mul_f32 v[238:239], v[74:75], v[142:143] op_sel_hi:[1,0]
	v_pk_fma_f32 v[236:237], v[236:237], v[0:1], v[120:121]
	v_pk_fma_f32 v[238:239], v[238:239], v[2:3], v[122:123]
	v_cvt_pk_bf16_f32 v246, v236, v237
	v_cvt_pk_bf16_f32 v247, v238, v239
	global_store_dwordx4 v[138:139], v[244:247], off offset:0
	global_store_dwordx4 v[214:215], v[172:175], off offset:528
	global_store_dwordx4 v[214:215], v[176:179], off offset:512
	v_pk_mul_f32 v[236:237], v[176:177], v[142:143] op_sel_hi:[1,0]
	v_pk_mul_f32 v[238:239], v[178:179], v[142:143] op_sel_hi:[1,0]
	v_pk_fma_f32 v[236:237], v[236:237], v[12:13], v[158:159]
	v_pk_fma_f32 v[238:239], v[238:239], v[14:15], v[160:161]
	v_cvt_pk_bf16_f32 v248, v236, v237
	v_cvt_pk_bf16_f32 v249, v238, v239
	v_pk_mul_f32 v[236:237], v[172:173], v[142:143] op_sel_hi:[1,0]
	v_pk_mul_f32 v[238:239], v[174:175], v[142:143] op_sel_hi:[1,0]
	v_pk_fma_f32 v[236:237], v[236:237], v[8:9], v[154:155]
	v_pk_fma_f32 v[238:239], v[238:239], v[10:11], v[156:157]
	v_cvt_pk_bf16_f32 v250, v236, v237
	v_cvt_pk_bf16_f32 v251, v238, v239
	global_store_dwordx4 v[138:139], v[248:251], off offset:256
	s_mov_b64 s[0:1], 0xb0000
	v_lshl_add_u64 v[212:213], v[162:163], 0, s[0:1]
	s_mov_b64 s[0:1], 0x58000
	v_lshl_add_u64 v[136:137], v[140:141], 0, s[0:1]
	global_store_dwordx4 v[212:213], v[60:63], off offset:16
	global_store_dwordx4 v[212:213], v[68:71], off offset:0
	v_pk_mul_f32 v[236:237], v[68:69], v[144:145] op_sel_hi:[1,0]
	v_pk_mul_f32 v[238:239], v[70:71], v[144:145] op_sel_hi:[1,0]
	v_pk_fma_f32 v[236:237], v[236:237], v[4:5], v[124:125]
	v_pk_fma_f32 v[238:239], v[238:239], v[6:7], v[126:127]
	v_cvt_pk_bf16_f32 v244, v236, v237
	v_cvt_pk_bf16_f32 v245, v238, v239
	v_pk_mul_f32 v[236:237], v[60:61], v[144:145] op_sel_hi:[1,0]
	v_pk_mul_f32 v[238:239], v[62:63], v[144:145] op_sel_hi:[1,0]
	v_pk_fma_f32 v[236:237], v[236:237], v[0:1], v[120:121]
	v_pk_fma_f32 v[238:239], v[238:239], v[2:3], v[122:123]
	v_cvt_pk_bf16_f32 v246, v236, v237
	v_cvt_pk_bf16_f32 v247, v238, v239
	global_store_dwordx4 v[136:137], v[244:247], off offset:0
	global_store_dwordx4 v[212:213], v[164:167], off offset:528
	global_store_dwordx4 v[212:213], v[168:171], off offset:512
	v_pk_mul_f32 v[236:237], v[168:169], v[144:145] op_sel_hi:[1,0]
	v_pk_mul_f32 v[238:239], v[170:171], v[144:145] op_sel_hi:[1,0]
	v_pk_fma_f32 v[236:237], v[236:237], v[12:13], v[158:159]
	v_pk_fma_f32 v[238:239], v[238:239], v[14:15], v[160:161]
	v_cvt_pk_bf16_f32 v248, v236, v237
	v_cvt_pk_bf16_f32 v249, v238, v239
	v_pk_mul_f32 v[236:237], v[164:165], v[144:145] op_sel_hi:[1,0]
	v_pk_mul_f32 v[238:239], v[166:167], v[144:145] op_sel_hi:[1,0]
	v_pk_fma_f32 v[236:237], v[236:237], v[8:9], v[154:155]
	v_pk_fma_f32 v[238:239], v[238:239], v[10:11], v[156:157]
	v_cvt_pk_bf16_f32 v250, v236, v237
	v_cvt_pk_bf16_f32 v251, v238, v239
	global_store_dwordx4 v[136:137], v[248:251], off offset:256
.Lfz_l1:
	s_mov_b32 s32, 3
	s_mov_b32 s2, s96
	s_mov_b32 s3, s97
	s_branch .LBB0_771

.LBB0_178:
	v_writelane_b32 v252, s2, 23
	s_and_b64 s[0:1], s[2:3], exec
	s_waitcnt vmcnt(2)
	v_mov_b32_e32 v0, v197
	v_writelane_b32 v252, s3, 24
	v_readlane_b32 s0, v253, 8
	v_readlane_b32 s1, v253, 9
	s_cselect_b32 s1, s1, s95
	s_cselect_b32 s0, s0, s94
	v_writelane_b32 v252, s0, 25
	v_readlane_b32 s6, v253, 14
	v_readlane_b32 s7, v253, 15
	v_writelane_b32 v252, s1, 26
	s_mov_b64 s[0:1], 0
	v_readlane_b32 s2, v253, 10
	v_ashrrev_i32_e32 v1, 6, v0
	v_add_u32_e32 v36, s58, v1
	v_cmp_gt_i32_e32 vcc, s71, v36
	v_readlane_b32 s28, v252, 23
	v_readlane_b32 s29, v252, 24
	s_nop 3
	s_and_b64 vcc, vcc, s[28:29]
	v_readlane_b32 s3, v253, 11
	v_readlane_b32 s4, v253, 12
	v_readlane_b32 s5, v253, 13
	v_readlane_b32 s8, v253, 16
	v_readlane_b32 s9, v253, 17
	v_readlane_b32 s10, v253, 18
	v_readlane_b32 s11, v253, 19
	v_readlane_b32 s12, v253, 20
	v_readlane_b32 s13, v253, 21
	v_readlane_b32 s14, v253, 22
	v_readlane_b32 s15, v253, 23
	s_and_saveexec_b64 s[6:7], vcc
	s_cbranch_execz .LBB0_189
	s_add_u32 s2, s96, s0
	s_mul_i32 s90, s76, 0x3000
	s_addc_u32 s3, s97, s1
	s_lshl_b64 s[0:1], s[90:91], 2
	s_add_u32 s0, s2, s0
	s_addc_u32 s1, s3, s1
	s_add_u32 s8, s0, 0x10ac0000
	s_addc_u32 s9, s1, 0
	v_lshlrev_b32_e32 v0, 2, v0
	v_cmp_lt_i32_e32 vcc, v230, v219
	s_add_u32 s10, s2, 0xb000000
	v_and_b32_e32 v38, 0xfc, v0
	v_cndmask_b32_e32 v0, v218, v230, vcc
	v_cmp_lt_i32_e32 vcc, v229, v219
	s_addc_u32 s11, s3, 0
	s_lshl_b32 s90, s76, 10
	v_readlane_b32 s12, v253, 8
	v_lshlrev_b32_e32 v39, 2, v0
	v_cndmask_b32_e32 v0, v218, v229, vcc
	v_cmp_lt_i32_e32 vcc, v226, v219
	s_lshl_b64 s[0:1], s[90:91], 2
	v_readlane_b32 s18, v253, 14
	v_lshlrev_b32_e32 v45, 2, v0
	v_cndmask_b32_e32 v0, v218, v226, vcc
	v_cmp_lt_i32_e32 vcc, v224, v219
	v_readlane_b32 s19, v253, 15
	s_add_u32 s0, s18, s0
	v_readlane_b32 s2, v252, 25
	v_lshlrev_b32_e32 v47, 2, v0
	v_cndmask_b32_e32 v0, v218, v224, vcc
	v_cmp_lt_i32_e32 vcc, v223, v219
	s_addc_u32 s1, s19, s1
	v_lshlrev_b32_e32 v194, 2, v38
	v_readlane_b32 s3, v252, 26
	v_lshlrev_b32_e32 v49, 2, v0
	v_cndmask_b32_e32 v0, v218, v223, vcc
	v_cmp_lt_i32_e32 vcc, v222, v219
	v_readlane_b32 s13, v253, 9
	v_lshl_add_u64 v[40:41], s[2:3], 0, v[194:195]
	v_lshlrev_b32_e32 v64, 2, v0
	v_cndmask_b32_e32 v0, v218, v222, vcc
	v_lshl_add_u64 v[42:43], s[0:1], 0, v[194:195]
	v_lshlrev_b32_e32 v194, 1, v38
	v_lshlrev_b32_e32 v65, 2, v0
	v_or_b32_e32 v44, 0x100, v38
	v_or_b32_e32 v46, 0x200, v38
	v_or_b32_e32 v48, 0x300, v38
	v_lshl_add_u64 v[50:51], s[10:11], 0, v[194:195]
	s_mov_b64 s[12:13], 0
	v_lshlrev_b32_e32 v194, 2, v38
	v_readlane_b32 s14, v253, 10
	v_readlane_b32 s15, v253, 11
	v_readlane_b32 s16, v253, 12
	v_readlane_b32 s17, v253, 13
	v_readlane_b32 s20, v253, 16
	v_readlane_b32 s21, v253, 17
	v_readlane_b32 s22, v253, 18
	v_readlane_b32 s23, v253, 19
	v_readlane_b32 s24, v253, 20
	v_readlane_b32 s25, v253, 21
	v_readlane_b32 s26, v253, 22
	v_readlane_b32 s27, v253, 23
	s_branch .LBB0_181

.LBB0_766:
	s_add_u32 s10, s8, 0xfffc0080
	s_addc_u32 s11, s9, -1
	s_add_i32 s38, 0, 0x10000
	v_add_u32_e32 v146, s38, v151
	ds_read_b128 v[120:123], v146
	ds_read_b128 v[124:127], v146 offset:1024
	ds_read_b128 v[142:145], v146 offset:2048
	ds_read_b128 v[146:149], v146 offset:3072
	s_cmp_eq_u32 s37, 12
	s_cselect_b32 s13, s1, s11
	s_cselect_b32 s12, s0, s10
	s_cselect_b32 s11, s7, s36
	s_cselect_b32 s10, s6, s35
	v_lshl_add_u64 v[186:187], s[8:9], 0, v[138:139]
	s_add_i32 m0, s20, 0xc000
	ds_read_b128 v[154:157], v153
	ds_read_b128 v[158:161], v153 offset:1024
	ds_read_b128 v[162:165], v153 offset:2048
	ds_read_b128 v[166:169], v153 offset:3072
	ds_read_b128 v[170:173], v153 offset:4096
	ds_read_b128 v[174:177], v153 offset:5120
	ds_read_b128 v[178:181], v153 offset:6144
	ds_read_b128 v[182:185], v153 offset:7168
	global_load_lds_dwordx4 v[186:187], off
	v_lshl_add_u64 v[186:187], s[8:9], 0, v[140:141]
	s_add_i32 m0, s20, 0xe000
	s_nop 0
	global_load_lds_dwordx4 v[186:187], off
	s_waitcnt lgkmcnt(8)
	s_barrier
	s_waitcnt lgkmcnt(0)
	s_setprio 1
	s_waitcnt lgkmcnt(0)
	v_mfma_f32_16x16x32_bf16 v[132:135], v[120:123], v[154:157], v[132:135]
	v_mfma_f32_16x16x32_bf16 v[128:131], v[142:145], v[154:157], v[128:131]
	v_mfma_f32_16x16x32_bf16 v[116:119], v[120:123], v[162:165], v[116:119]
	v_mfma_f32_16x16x32_bf16 v[112:115], v[142:145], v[162:165], v[112:115]
	v_mfma_f32_16x16x32_bf16 v[108:111], v[120:123], v[170:173], v[108:111]
	v_mfma_f32_16x16x32_bf16 v[104:107], v[142:145], v[170:173], v[104:107]
	v_mfma_f32_16x16x32_bf16 v[100:103], v[120:123], v[178:181], v[100:103]
	v_mfma_f32_16x16x32_bf16 v[96:99], v[142:145], v[178:181], v[96:99]
	v_mfma_f32_16x16x32_bf16 v[132:135], v[124:127], v[158:161], v[132:135]
	v_mfma_f32_16x16x32_bf16 v[128:131], v[146:149], v[158:161], v[128:131]
	v_mfma_f32_16x16x32_bf16 v[116:119], v[124:127], v[166:169], v[116:119]
	v_mfma_f32_16x16x32_bf16 v[112:115], v[146:149], v[166:169], v[112:115]
	v_mfma_f32_16x16x32_bf16 v[108:111], v[124:127], v[174:177], v[108:111]
	v_mfma_f32_16x16x32_bf16 v[104:107], v[146:149], v[174:177], v[104:107]
	v_mfma_f32_16x16x32_bf16 v[100:103], v[124:127], v[182:185], v[100:103]
	v_mfma_f32_16x16x32_bf16 v[96:99], v[146:149], v[182:185], v[96:99]
	s_setprio 0
	s_barrier
	s_add_i32 s40, 0, 0x14000
	s_add_i32 s38, s38, s19
	v_add_u32_e32 v208, s40, v151
	v_lshl_add_u64 v[212:213], s[10:11], 0, v[194:195]
	s_mov_b32 m0, s38
	ds_read_b128 v[186:189], v208
	ds_read_b128 v[190:193], v208 offset:1024
	ds_read_b128 v[204:207], v208 offset:2048
	ds_read_b128 v[208:211], v208 offset:3072
	global_load_lds_dwordx4 v[212:213], off
	v_lshl_add_u64 v[214:215], s[10:11], 0, v[136:137]
	s_add_i32 m0, s38, 0x2000
	s_nop 0
	global_load_lds_dwordx4 v[214:215], off
	s_barrier
	s_waitcnt lgkmcnt(0)
	s_setprio 1
	s_waitcnt lgkmcnt(0)
	v_mfma_f32_16x16x32_bf16 v[64:67], v[186:189], v[154:157], v[64:67]
	v_mfma_f32_16x16x32_bf16 v[56:59], v[204:207], v[154:157], v[56:59]
	v_mfma_f32_16x16x32_bf16 v[52:55], v[186:189], v[162:165], v[52:55]
	v_mfma_f32_16x16x32_bf16 v[48:51], v[204:207], v[162:165], v[48:51]
	v_mfma_f32_16x16x32_bf16 v[44:47], v[186:189], v[170:173], v[44:47]
	v_mfma_f32_16x16x32_bf16 v[40:43], v[204:207], v[170:173], v[40:43]
	v_mfma_f32_16x16x32_bf16 v[36:39], v[186:189], v[178:181], v[36:39]
	v_mfma_f32_16x16x32_bf16 v[32:35], v[204:207], v[178:181], v[32:35]
	v_mfma_f32_16x16x32_bf16 v[64:67], v[190:193], v[158:161], v[64:67]
	v_mfma_f32_16x16x32_bf16 v[56:59], v[208:211], v[158:161], v[56:59]
	v_mfma_f32_16x16x32_bf16 v[52:55], v[190:193], v[166:169], v[52:55]
	v_mfma_f32_16x16x32_bf16 v[48:51], v[208:211], v[166:169], v[48:51]
	v_mfma_f32_16x16x32_bf16 v[44:47], v[190:193], v[174:177], v[44:47]
	v_mfma_f32_16x16x32_bf16 v[40:43], v[208:211], v[174:177], v[40:43]
	v_mfma_f32_16x16x32_bf16 v[36:39], v[190:193], v[182:185], v[36:39]
	v_mfma_f32_16x16x32_bf16 v[32:35], v[208:211], v[182:185], v[32:35]
	s_setprio 0
	s_mov_b32 m0, s20
	v_lshl_add_u64 v[216:217], s[12:13], 0, v[194:195]
	s_barrier
	ds_read_b128 v[154:157], v153 offset:16384
	ds_read_b128 v[158:161], v153 offset:17408
	ds_read_b128 v[162:165], v153 offset:18432
	ds_read_b128 v[166:169], v153 offset:19456
	ds_read_b128 v[170:173], v153 offset:20480
	ds_read_b128 v[174:177], v153 offset:21504
	ds_read_b128 v[178:181], v153 offset:22528
	ds_read_b128 v[182:185], v153 offset:23552
	global_load_lds_dwordx4 v[216:217], off
	v_lshl_add_u64 v[236:237], s[12:13], 0, v[136:137]
	s_mov_b32 m0, s21
	s_nop 0
	global_load_lds_dwordx4 v[236:237], off
	s_barrier
	s_waitcnt lgkmcnt(0)
	s_setprio 1
	s_waitcnt lgkmcnt(0)
	v_mfma_f32_16x16x32_bf16 v[92:95], v[120:123], v[154:157], v[92:95]
	v_mfma_f32_16x16x32_bf16 v[88:91], v[142:145], v[154:157], v[88:91]
	v_mfma_f32_16x16x32_bf16 v[84:87], v[120:123], v[162:165], v[84:87]
	v_mfma_f32_16x16x32_bf16 v[80:83], v[142:145], v[162:165], v[80:83]
	v_mfma_f32_16x16x32_bf16 v[76:79], v[120:123], v[170:173], v[76:79]
	v_mfma_f32_16x16x32_bf16 v[72:75], v[142:145], v[170:173], v[72:75]
	v_mfma_f32_16x16x32_bf16 v[68:71], v[120:123], v[178:181], v[68:71]
	v_mfma_f32_16x16x32_bf16 v[60:63], v[142:145], v[178:181], v[60:63]
	v_mfma_f32_16x16x32_bf16 v[92:95], v[124:127], v[158:161], v[92:95]
	v_mfma_f32_16x16x32_bf16 v[88:91], v[146:149], v[158:161], v[88:91]
	v_mfma_f32_16x16x32_bf16 v[84:87], v[124:127], v[166:169], v[84:87]
	v_mfma_f32_16x16x32_bf16 v[80:83], v[146:149], v[166:169], v[80:83]
	v_mfma_f32_16x16x32_bf16 v[76:79], v[124:127], v[174:177], v[76:79]
	v_mfma_f32_16x16x32_bf16 v[72:75], v[146:149], v[174:177], v[72:75]
	v_mfma_f32_16x16x32_bf16 v[68:71], v[124:127], v[182:185], v[68:71]
	v_mfma_f32_16x16x32_bf16 v[60:63], v[146:149], v[182:185], v[60:63]
	s_setprio 0
	s_barrier
	s_add_u32 s38, s10, 0x40000
	s_addc_u32 s39, s11, 0
	s_add_i32 s40, s40, s19
	v_lshl_add_u64 v[120:121], s[38:39], 0, v[194:195]
	s_mov_b32 m0, s40
	s_nop 0
	global_load_lds_dwordx4 v[120:121], off
	v_lshl_add_u64 v[120:121], s[38:39], 0, v[136:137]
	s_add_i32 m0, s40, 0x2000
	s_nop 0
	global_load_lds_dwordx4 v[120:121], off
	s_waitcnt vmcnt(6)
	s_barrier
	s_setprio 1
	v_mfma_f32_16x16x32_bf16 v[28:31], v[186:189], v[154:157], v[28:31]
	v_mfma_f32_16x16x32_bf16 v[24:27], v[204:207], v[154:157], v[24:27]
	v_mfma_f32_16x16x32_bf16 v[20:23], v[186:189], v[162:165], v[20:23]
	v_mfma_f32_16x16x32_bf16 v[16:19], v[204:207], v[162:165], v[16:19]
	v_mfma_f32_16x16x32_bf16 v[12:15], v[186:189], v[170:173], v[12:15]
	v_mfma_f32_16x16x32_bf16 v[8:11], v[204:207], v[170:173], v[8:11]
	v_mfma_f32_16x16x32_bf16 v[4:7], v[186:189], v[178:181], v[4:7]
	v_mfma_f32_16x16x32_bf16 v[0:3], v[204:207], v[178:181], v[0:3]
	v_mfma_f32_16x16x32_bf16 v[28:31], v[190:193], v[158:161], v[28:31]
	v_mfma_f32_16x16x32_bf16 v[24:27], v[208:211], v[158:161], v[24:27]
	v_mfma_f32_16x16x32_bf16 v[20:23], v[190:193], v[166:169], v[20:23]
	v_mfma_f32_16x16x32_bf16 v[16:19], v[208:211], v[166:169], v[16:19]
	v_mfma_f32_16x16x32_bf16 v[12:15], v[190:193], v[174:177], v[12:15]
	v_mfma_f32_16x16x32_bf16 v[8:11], v[208:211], v[174:177], v[8:11]
	v_mfma_f32_16x16x32_bf16 v[4:7], v[190:193], v[182:185], v[4:7]
	v_mfma_f32_16x16x32_bf16 v[0:3], v[208:211], v[182:185], v[0:3]
	s_setprio 0
	s_add_i32 s38, 0, 0x18000
	v_add_u32_e32 v146, s38, v151
	s_barrier
	ds_read_b128 v[120:123], v146
	ds_read_b128 v[124:127], v146 offset:1024
	ds_read_b128 v[142:145], v146 offset:2048
	ds_read_b128 v[146:149], v146 offset:3072
	s_add_u32 s12, s12, 0x40000
	s_addc_u32 s13, s13, 0
	s_mov_b32 m0, s22
	v_lshl_add_u64 v[186:187], s[12:13], 0, v[194:195]
	ds_read_b128 v[154:157], v153 offset:32768
	ds_read_b128 v[158:161], v153 offset:33792
	ds_read_b128 v[162:165], v153 offset:34816
	ds_read_b128 v[166:169], v153 offset:35840
	ds_read_b128 v[170:173], v153 offset:36864
	ds_read_b128 v[174:177], v153 offset:37888
	ds_read_b128 v[178:181], v153 offset:38912
	ds_read_b128 v[182:185], v153 offset:39936
	global_load_lds_dwordx4 v[186:187], off
	v_lshl_add_u64 v[186:187], s[12:13], 0, v[136:137]
	s_mov_b32 m0, s23
	s_nop 0
	global_load_lds_dwordx4 v[186:187], off
	s_waitcnt lgkmcnt(8)
	s_barrier
	s_waitcnt lgkmcnt(0)
	s_setprio 1
	s_waitcnt lgkmcnt(0)
	v_mfma_f32_16x16x32_bf16 v[132:135], v[120:123], v[154:157], v[132:135]
	v_mfma_f32_16x16x32_bf16 v[128:131], v[142:145], v[154:157], v[128:131]
	v_mfma_f32_16x16x32_bf16 v[116:119], v[120:123], v[162:165], v[116:119]
	v_mfma_f32_16x16x32_bf16 v[112:115], v[142:145], v[162:165], v[112:115]
	v_mfma_f32_16x16x32_bf16 v[108:111], v[120:123], v[170:173], v[108:111]
	v_mfma_f32_16x16x32_bf16 v[104:107], v[142:145], v[170:173], v[104:107]
	v_mfma_f32_16x16x32_bf16 v[100:103], v[120:123], v[178:181], v[100:103]
	v_mfma_f32_16x16x32_bf16 v[96:99], v[142:145], v[178:181], v[96:99]
	v_mfma_f32_16x16x32_bf16 v[132:135], v[124:127], v[158:161], v[132:135]
	v_mfma_f32_16x16x32_bf16 v[128:131], v[146:149], v[158:161], v[128:131]
	v_mfma_f32_16x16x32_bf16 v[116:119], v[124:127], v[166:169], v[116:119]
	v_mfma_f32_16x16x32_bf16 v[112:115], v[146:149], v[166:169], v[112:115]
	v_mfma_f32_16x16x32_bf16 v[108:111], v[124:127], v[174:177], v[108:111]
	v_mfma_f32_16x16x32_bf16 v[104:107], v[146:149], v[174:177], v[104:107]
	v_mfma_f32_16x16x32_bf16 v[100:103], v[124:127], v[182:185], v[100:103]
	v_mfma_f32_16x16x32_bf16 v[96:99], v[146:149], v[182:185], v[96:99]
	s_setprio 0
	s_barrier
	s_add_i32 s12, 0, 0x1c000
	s_add_i32 s13, s38, s19
	v_add_u32_e32 v208, s12, v151
	v_lshl_add_u64 v[212:213], v[212:213], 0, s[82:83]
	s_mov_b32 m0, s13
	ds_read_b128 v[186:189], v208
	ds_read_b128 v[190:193], v208 offset:1024
	ds_read_b128 v[204:207], v208 offset:2048
	ds_read_b128 v[208:211], v208 offset:3072
	global_load_lds_dwordx4 v[212:213], off
	v_lshl_add_u64 v[212:213], v[214:215], 0, s[82:83]
	s_add_i32 m0, s13, 0x2000
	s_nop 0
	global_load_lds_dwordx4 v[212:213], off
	s_barrier
	s_waitcnt lgkmcnt(0)
	s_setprio 1
	s_waitcnt lgkmcnt(0)
	v_mfma_f32_16x16x32_bf16 v[64:67], v[186:189], v[154:157], v[64:67]
	v_mfma_f32_16x16x32_bf16 v[56:59], v[204:207], v[154:157], v[56:59]
	v_mfma_f32_16x16x32_bf16 v[52:55], v[186:189], v[162:165], v[52:55]
	v_mfma_f32_16x16x32_bf16 v[48:51], v[204:207], v[162:165], v[48:51]
	v_mfma_f32_16x16x32_bf16 v[44:47], v[186:189], v[170:173], v[44:47]
	v_mfma_f32_16x16x32_bf16 v[40:43], v[204:207], v[170:173], v[40:43]
	v_mfma_f32_16x16x32_bf16 v[36:39], v[186:189], v[178:181], v[36:39]
	v_mfma_f32_16x16x32_bf16 v[32:35], v[204:207], v[178:181], v[32:35]
	v_mfma_f32_16x16x32_bf16 v[64:67], v[190:193], v[158:161], v[64:67]
	v_mfma_f32_16x16x32_bf16 v[56:59], v[208:211], v[158:161], v[56:59]
	v_mfma_f32_16x16x32_bf16 v[52:55], v[190:193], v[166:169], v[52:55]
	v_mfma_f32_16x16x32_bf16 v[48:51], v[208:211], v[166:169], v[48:51]
	v_mfma_f32_16x16x32_bf16 v[44:47], v[190:193], v[174:177], v[44:47]
	v_mfma_f32_16x16x32_bf16 v[40:43], v[208:211], v[174:177], v[40:43]
	v_mfma_f32_16x16x32_bf16 v[36:39], v[190:193], v[182:185], v[36:39]
	v_mfma_f32_16x16x32_bf16 v[32:35], v[208:211], v[182:185], v[32:35]
	s_setprio 0
	s_mov_b32 m0, s26
	v_lshl_add_u64 v[212:213], v[216:217], 0, s[82:83]
	s_barrier
	ds_read_b128 v[154:157], v153 offset:49152
	ds_read_b128 v[158:161], v153 offset:50176
	ds_read_b128 v[162:165], v153 offset:51200
	ds_read_b128 v[166:169], v153 offset:52224
	ds_read_b128 v[170:173], v153 offset:53248
	ds_read_b128 v[174:177], v153 offset:54272
	ds_read_b128 v[178:181], v153 offset:55296
	ds_read_b128 v[182:185], v153 offset:56320
	global_load_lds_dwordx4 v[212:213], off
	v_lshl_add_u64 v[212:213], v[236:237], 0, s[82:83]
	s_mov_b32 m0, s27
	s_nop 0
	global_load_lds_dwordx4 v[212:213], off
	s_barrier
	s_waitcnt lgkmcnt(0)
	s_setprio 1
	s_waitcnt lgkmcnt(0)
	v_mfma_f32_16x16x32_bf16 v[92:95], v[120:123], v[154:157], v[92:95]
	v_mfma_f32_16x16x32_bf16 v[88:91], v[142:145], v[154:157], v[88:91]
	v_mfma_f32_16x16x32_bf16 v[84:87], v[120:123], v[162:165], v[84:87]
	v_mfma_f32_16x16x32_bf16 v[80:83], v[142:145], v[162:165], v[80:83]
	v_mfma_f32_16x16x32_bf16 v[76:79], v[120:123], v[170:173], v[76:79]
	v_mfma_f32_16x16x32_bf16 v[72:75], v[142:145], v[170:173], v[72:75]
	v_mfma_f32_16x16x32_bf16 v[68:71], v[120:123], v[178:181], v[68:71]
	v_mfma_f32_16x16x32_bf16 v[60:63], v[142:145], v[178:181], v[60:63]
	v_mfma_f32_16x16x32_bf16 v[92:95], v[124:127], v[158:161], v[92:95]
	v_mfma_f32_16x16x32_bf16 v[88:91], v[146:149], v[158:161], v[88:91]
	v_mfma_f32_16x16x32_bf16 v[84:87], v[124:127], v[166:169], v[84:87]
	v_mfma_f32_16x16x32_bf16 v[80:83], v[146:149], v[166:169], v[80:83]
	v_mfma_f32_16x16x32_bf16 v[76:79], v[124:127], v[174:177], v[76:79]
	v_mfma_f32_16x16x32_bf16 v[72:75], v[146:149], v[174:177], v[72:75]
	v_mfma_f32_16x16x32_bf16 v[68:71], v[124:127], v[182:185], v[68:71]
	v_mfma_f32_16x16x32_bf16 v[60:63], v[146:149], v[182:185], v[60:63]
	s_setprio 0
	s_barrier
	s_add_u32 s10, s10, 0x40080
	s_addc_u32 s11, s11, 0
	s_add_i32 s12, s12, s19
	v_lshl_add_u64 v[120:121], s[10:11], 0, v[194:195]
	s_mov_b32 m0, s12
	s_nop 0
	global_load_lds_dwordx4 v[120:121], off
	v_lshl_add_u64 v[120:121], s[10:11], 0, v[136:137]
	s_add_i32 m0, s12, 0x2000
	s_nop 0
	global_load_lds_dwordx4 v[120:121], off
	s_waitcnt vmcnt(6)
	s_barrier
	s_setprio 1
	v_mfma_f32_16x16x32_bf16 v[28:31], v[186:189], v[154:157], v[28:31]
	v_mfma_f32_16x16x32_bf16 v[24:27], v[204:207], v[154:157], v[24:27]
	v_mfma_f32_16x16x32_bf16 v[20:23], v[186:189], v[162:165], v[20:23]
	v_mfma_f32_16x16x32_bf16 v[16:19], v[204:207], v[162:165], v[16:19]
	v_mfma_f32_16x16x32_bf16 v[12:15], v[186:189], v[170:173], v[12:15]
	v_mfma_f32_16x16x32_bf16 v[8:11], v[204:207], v[170:173], v[8:11]
	v_mfma_f32_16x16x32_bf16 v[4:7], v[186:189], v[178:181], v[4:7]
	v_mfma_f32_16x16x32_bf16 v[0:3], v[204:207], v[178:181], v[0:3]
	v_mfma_f32_16x16x32_bf16 v[28:31], v[190:193], v[158:161], v[28:31]
	v_mfma_f32_16x16x32_bf16 v[24:27], v[208:211], v[158:161], v[24:27]
	v_mfma_f32_16x16x32_bf16 v[20:23], v[190:193], v[166:169], v[20:23]
	v_mfma_f32_16x16x32_bf16 v[16:19], v[208:211], v[166:169], v[16:19]
	v_mfma_f32_16x16x32_bf16 v[12:15], v[190:193], v[174:177], v[12:15]
	v_mfma_f32_16x16x32_bf16 v[8:11], v[208:211], v[174:177], v[8:11]
	v_mfma_f32_16x16x32_bf16 v[4:7], v[190:193], v[182:185], v[4:7]
	v_mfma_f32_16x16x32_bf16 v[0:3], v[208:211], v[182:185], v[0:3]
	s_setprio 0
	s_add_i32 s37, s37, 2
	s_add_u32 s8, s8, 0x100
	s_addc_u32 s9, s9, 0
	s_add_u32 s35, s35, 0x100
	s_addc_u32 s36, s36, 0
	s_cmp_gt_u32 s37, 13
	s_barrier
	s_cbranch_scc0 .LBB0_766
	s_lshr_b32 s8, s31, 4
	s_mulk_i32 s8, 0xc00
	s_ashr_i32 s9, s8, 31
	v_lshl_or_b32 v120, s34, 8, v152
	s_lshl_b64 s[8:9], s[8:9], 2
	s_add_u32 s8, s24, s8
	v_ashrrev_i32_e32 v121, 31, v120
	v_lshl_add_u32 v148, s31, 8, v150
	s_addc_u32 s9, s25, s9
	v_lshlrev_b64 v[146:147], 2, v[120:121]
	v_lshl_add_u64 v[142:143], s[8:9], 0, v[146:147]
	v_ashrrev_i32_e32 v149, 31, v148
	v_readlane_b32 s8, v252, 25
	v_lshlrev_b64 v[162:163], 12, v[148:149]
	v_readlane_b32 s9, v252, 26
	s_cmpk_gt_u32 s14, 0xff
	s_cbranch_scc1 .Lfz_al
	s_barrier

.Lfz_nord:
	v_mov_b32_e32 v164, v0
	v_mov_b32_e32 v165, v1
	v_mov_b32_e32 v166, v2
	v_mov_b32_e32 v167, v3
	v_mov_b32_e32 v168, v4
	v_mov_b32_e32 v169, v5
	v_mov_b32_e32 v170, v6
	v_mov_b32_e32 v171, v7
	v_mov_b32_e32 v172, v8
	v_mov_b32_e32 v173, v9
	v_mov_b32_e32 v174, v10
	v_mov_b32_e32 v175, v11
	v_mov_b32_e32 v176, v12
	v_mov_b32_e32 v177, v13
	v_mov_b32_e32 v178, v14
	v_mov_b32_e32 v179, v15
	v_mov_b32_e32 v180, v16
	v_mov_b32_e32 v181, v17
	v_mov_b32_e32 v182, v18
	v_mov_b32_e32 v183, v19
	s_mov_b32 s31, s30
	s_mov_b32 s34, s29
	s_mov_b64 s[10:11], s[6:7]
	s_mov_b64 s[8:9], s[0:1]
	s_and_b64 vcc, exec, s[4:5]
	s_waitcnt vmcnt(0)
	s_branch .LBB0_770
	s_cbranch_vccz .LBB0_763
	s_waitcnt vmcnt(0)
	s_cmpk_gt_u32 s14, 0xff
	s_cbranch_scc1 .LBB0_770
	s_barrier
